# SSD prompt-unit prologue: first chunk's conv-row loads issued before wave 0 waits for dt and runs SSD_PREP (one exposed round trip per unit instead of two)
# speedup vs baseline: 1.0072x; 1.0006x over previous
.LBB0_747:
	v_lshrrev_b32_e32 v202, 4, v201
	s_waitcnt vmcnt(2)
	v_mul_f32_e32 v2, 0x3fb8aa3b, v2
	s_lshl_b32 s54, s76, 4
	v_exp_f32_e32 v204, v2
	v_lshl_or_b32 v2, v202, 2, s54
	v_and_b32_e32 v105, 15, v1
	s_lshl_b32 s5, s5, 16
	v_mul_u32_u24_e32 v6, 0x48, v2
	s_add_i32 s77, s5, 0
	v_or_b32_e32 v7, v6, v105
	v_lshl_add_u32 v7, v7, 1, s77
	ds_write_b16 v7, v0 offset:46080
	v_mad_u32_u24 v7, v2, s86, s86
	v_add_u32_e32 v8, v7, v105
	v_lshl_add_u32 v8, v8, 1, s77
	ds_write_b16 v8, v0 offset:46080
	v_mad_u32_u24 v8, v2, s86, v234
	v_or_b32_e32 v9, v8, v105
	v_lshl_add_u32 v9, v9, 1, s77
	v_or_b32_e32 v3, 16, v105
	ds_write_b16 v9, v0 offset:46080
	v_mad_u32_u24 v9, v2, s86, v235
	v_add_u32_e32 v10, v9, v105
	v_or_b32_e32 v6, v6, v3
	v_lshl_add_u32 v10, v10, 1, s77
	v_lshl_add_u32 v6, v6, 1, s77
	ds_write_b16 v10, v0 offset:46080
	ds_write_b16 v6, v0 offset:46080
	v_add_u32_e32 v6, v7, v3
	v_lshl_add_u32 v6, v6, 1, s77
	ds_write_b16 v6, v0 offset:46080
	v_add_u32_e32 v6, v8, v3
	v_add_u32_e32 v3, v9, v3
	v_or_b32_e32 v4, 32, v105
	v_lshl_add_u32 v3, v3, 1, s77
	ds_write_b16 v3, v0 offset:46080
	v_mad_u32_u24 v3, v2, s86, v4
	v_lshl_add_u32 v6, v6, 1, s77
	v_lshl_add_u32 v3, v3, 1, s77
	ds_write_b16 v6, v0 offset:46080
	ds_write_b16 v3, v0 offset:46080
	v_add_u32_e32 v3, v7, v4
	v_lshl_add_u32 v3, v3, 1, s77
	ds_write_b16 v3, v0 offset:46080
	v_add_u32_e32 v3, v8, v4
	v_or_b32_e32 v5, 48, v105
	v_lshl_add_u32 v3, v3, 1, s77
	ds_write_b16 v3, v0 offset:46080
	v_add_u32_e32 v3, v9, v4
	v_mad_u32_u24 v2, v2, s86, v5
	v_lshl_add_u32 v3, v3, 1, s77
	v_lshl_add_u32 v2, v2, 1, s77
	ds_write_b16 v3, v0 offset:46080
	ds_write_b16 v2, v0 offset:46080
	v_add_u32_e32 v2, v7, v5
	v_lshl_add_u32 v2, v2, 1, s77
	ds_write_b16 v2, v0 offset:46080
	v_add_u32_e32 v2, v8, v5
	v_lshl_add_u32 v2, v2, 1, s77
	ds_write_b16 v2, v0 offset:46080
	v_add_u32_e32 v2, v9, v5
	v_cndmask_b32_e64 v3, 0, 1, s[10:11]
	v_lshl_add_u32 v2, v2, 1, s77
	v_cmp_ne_u32_e64 s[8:9], 1, v3
	s_andn2_b64 vcc, exec, s[10:11]
	ds_write_b16 v2, v0 offset:46080
.LBB0_749:
	s_add_u32 s50, s50, 0xb100000
	s_addc_u32 s51, s51, 0
	s_lshl_b32 s5, s62, 6
	s_cmp_eq_u32 s76, 1
	s_cselect_b32 s12, 0x400, s83
	v_lshrrev_b32_e32 v37, 3, v201
	v_and_b32_e32 v2, 7, v1
	s_or_b32 s18, s64, s12
	v_cndmask_b32_e64 v36, v2, v37, s[10:11]
	s_and_b64 s[12:13], s[10:11], exec
	s_cselect_b32 s12, s5, s18
	v_lshlrev_b32_e32 v38, 3, v36
	s_cmp_lg_u32 s76, 3
	v_or_b32_e32 v104, s12, v38
	s_cselect_b64 s[12:13], -1, 0
	v_cndmask_b32_e64 v39, v37, v2, s[10:11]
	s_and_b64 vcc, exec, s[12:13]
	s_cbranch_vccz .LBB0_757
	v_lshlrev_b32_e32 v205, 3, v39
	v_mov_b32_e32 v6, v0
	v_mov_b32_e32 v7, v0
	v_add3_u32 v44, s4, -2, v205
	v_mov_b32_e32 v4, v0
	v_mov_b32_e32 v5, v0
	v_mov_b64_e32 v[10:11], v[6:7]
	v_cmp_gt_u32_e32 vcc, s33, v44
	v_lshlrev_b32_e32 v2, 1, v104
	v_mov_b64_e32 v[8:9], v[4:5]
	s_and_saveexec_b64 s[52:53], vcc
	s_cbranch_execz .LBB0_752
	v_or_b32_e32 v3, s61, v44
	v_mov_b64_e32 v[8:9], s[50:51]
	v_mad_u64_u32 v[8:9], s[18:19], v3, s3, v[8:9]
	v_mov_b32_e32 v3, v0
	v_lshl_add_u64 v[8:9], v[8:9], 0, v[2:3]
	global_load_dwordx4 v[8:11], v[8:9], off offset:2048

.LBB0_759:
	s_andn2_b64 vcc, exec, s[10:11]
	s_cbranch_vccnz .Lprep_skip_p
	s_waitcnt vmcnt(0)
	v_add_f32_e32 v64, v189, v203
	v_mul_f32_e64 v65, |v64|, s87
	v_exp_f32_e32 v65, v65
	v_max_f32_e32 v64, 0, v64
	v_add_f32_e32 v65, 1.0, v65
	v_cmp_gt_f32_e32 vcc, s84, v65
	s_nop 1
	v_cndmask_b32_e64 v66, 0, 32, vcc
	v_ldexp_f32 v65, v65, v66
	v_log_f32_e32 v65, v65
	v_cndmask_b32_e32 v66, 0, v232, vcc
	v_mul_f32_e32 v67, 0x3f317217, v65
	v_fma_f32 v67, v65, s80, -v67
	v_fmac_f32_e32 v67, 0x3377d1cf, v65
	v_fmac_f32_e32 v67, 0x3f317217, v65
	v_cmp_lt_f32_e64 vcc, |v65|, s81
	s_nop 1
	v_cndmask_b32_e32 v65, v65, v67, vcc
	v_sub_f32_e32 v65, v65, v66
	v_cmp_ne_u32_e32 vcc, 0, v201
	v_add_f32_e32 v64, v64, v65
	v_mul_f32_e64 v65, v64, -v204
	s_nop 1
	v_add_f32_dpp v65, v65, v65 row_shr:1 row_mask:0xf bank_mask:0xf
	s_nop 1
	v_add_f32_dpp v65, v65, v65 row_shr:2 row_mask:0xf bank_mask:0xf
	s_nop 1
	v_add_f32_dpp v65, v65, v65 row_shr:4 row_mask:0xf bank_mask:0xf
	s_nop 1
	v_add_f32_dpp v65, v65, v65 row_shr:8 row_mask:0xf bank_mask:0xf
	s_nop 1
	v_add_f32_dpp v65, v65, v65 row_bcast:15 row_mask:0xa bank_mask:0xf
	s_nop 1
	v_add_f32_dpp v65, v65, v65 row_bcast:31 row_mask:0xc bank_mask:0xf
	v_lshl_add_u32 v66, v201, 2, s77
	v_readlane_b32 s96, v65, 63
	s_nop 1
	v_sub_f32_e32 v67, s96, v65
	v_fma_f32 v67, v64, -v204, v67
	v_cndmask_b32_e64 v65, v67, v65, s[6:7]
	ds_write2st64_b32 v66, v64, v65 offset0:252 offset1:253
